# GEMM steady K-loops: tile-end barrier hoisted before the last 3 MFMA groups (was 2), next-tile fragment reads under 12 MFMAs; otherwise as v48
# baseline (speedup 1.0000x reference)
; DEVI f32x4 mfma16(bf16x8 a, bf16x8 b, f32x4 c) { return __builtin_amdgcn_mfma_f32_16x16x32_bf16(a, b, c, 0, 0, 0); }
; template <int MODE, class Epi>
; DEVI void gemm256_phase(int sw, const bf16_t* __restrict__ W, int ldw, const bf16_t* __restrict__ X, int ldx, int K, int nN, char* shm, const Epi& epi) {
;     ...
; #pragma unroll
;       for (int ks = 0; ks < 2; ++ks) {
;         const int kx = (wid >> 2) ? (1 - 2 * ks) * 1024 : 0;
;         bf16x8 At[8], Bf[4];
; #pragma unroll
;         for (int m = 0; m < 8; ++m) At[m] = *(const bf16x8*)(SAp + (2 * m + ks) * 1024 + kx);
; #pragma unroll
;         for (int n = 0; n < 4; ++n) Bf[n] = *(const bf16x8*)(SBp + (2 * n + ks) * 1024 + kx);
; #pragma unroll
;         for (int m = 0; m < 8; ++m)
; #pragma unroll
;           for (int n = 0; n < 4; ++n) acc[m][n] = mfma16(At[m], Bf[n], acc[m][n]);
;         __builtin_amdgcn_sched_barrier(0);
;         if (ks == 0 && wid >= 4) {
;           if (st_own) stage(cur ^ 1, n0, m0, kt0 + t + 1);
;           else if (st_next) stage(cur ^ 1, n1, m1, kt1);
;         }
;       }
;       asm volatile("s_waitcnt vmcnt(0)" ::: "memory");
;       __syncthreads();
.LBB0_167:
.Lmy_xs_168:
	s_waitcnt lgkmcnt(3)
	v_mfma_f32_16x16x32_bf16 v[124:127], v[220:223], v[134:137], v[124:127]
	v_mfma_f32_16x16x32_bf16 v[120:123], v[220:223], v[138:141], v[120:123]
	v_mfma_f32_16x16x32_bf16 v[116:119], v[220:223], v[142:145], v[116:119]
	v_mfma_f32_16x16x32_bf16 v[112:115], v[220:223], v[146:149], v[112:115]
	ds_read_b128 v[236:239], v150 offset:9216
	s_waitcnt lgkmcnt(3)
	v_mfma_f32_16x16x32_bf16 v[108:111], v[224:227], v[134:137], v[108:111]
	v_mfma_f32_16x16x32_bf16 v[104:107], v[224:227], v[138:141], v[104:107]
	v_mfma_f32_16x16x32_bf16 v[100:103], v[224:227], v[142:145], v[100:103]
	v_mfma_f32_16x16x32_bf16 v[96:99], v[224:227], v[146:149], v[96:99]
	ds_read_b128 v[240:243], v150 offset:11264
	s_waitcnt lgkmcnt(3)
	v_mfma_f32_16x16x32_bf16 v[92:95], v[228:231], v[134:137], v[92:95]
	v_mfma_f32_16x16x32_bf16 v[88:91], v[228:231], v[138:141], v[88:91]
	v_mfma_f32_16x16x32_bf16 v[84:87], v[228:231], v[142:145], v[84:87]
	v_mfma_f32_16x16x32_bf16 v[80:83], v[228:231], v[146:149], v[80:83]
	ds_read_b128 v[244:247], v150 offset:13312
	s_waitcnt lgkmcnt(3)
	v_mfma_f32_16x16x32_bf16 v[76:79], v[232:235], v[134:137], v[76:79]
	v_mfma_f32_16x16x32_bf16 v[72:75], v[232:235], v[138:141], v[72:75]
	v_mfma_f32_16x16x32_bf16 v[68:71], v[232:235], v[142:145], v[68:71]
	v_mfma_f32_16x16x32_bf16 v[64:67], v[232:235], v[146:149], v[64:67]
	ds_read_b128 v[248:251], v150 offset:15360
	s_waitcnt lgkmcnt(3)
	v_mfma_f32_16x16x32_bf16 v[60:63], v[236:239], v[134:137], v[60:63]
	v_mfma_f32_16x16x32_bf16 v[56:59], v[236:239], v[138:141], v[56:59]
	v_mfma_f32_16x16x32_bf16 v[52:55], v[236:239], v[142:145], v[52:55]
	v_mfma_f32_16x16x32_bf16 v[48:51], v[236:239], v[146:149], v[48:51]
	s_addk_i32 s67, 0x80
	s_cmp_eq_u32 s66, s68
	s_cbranch_scc1 .Lmy_xexit_168
	s_add_i32 s0, s45, s68
	s_and_b32 s69, s0, 1
	s_add_i32 s68, s68, 1
	s_cmp_lt_i32 s68, s46
	s_cselect_b64 s[0:1], -1, 0
	s_cmp_ge_i32 s68, s46
	s_cselect_b64 s[8:9], -1, 0
	v_cndmask_b32_e64 v128, 0, 1, s[0:1]
	s_and_b64 s[8:9], s[2:3], s[8:9]
	s_andn2_b64 vcc, exec, s[36:37]
	v_cmp_ne_u32_e64 s[0:1], 1, v128
	s_lshl_b32 s10, s69, 16
	s_add_i32 s11, s10, s47
	v_add_u32_e32 v129, s11, v194
	v_add_u32_e32 v253, s53, v129
	s_or_b32 s11, s10, s52
	v_add_u32_e32 v128, s11, v194
	v_add_u32_e32 v252, s53, v128
	s_waitcnt lgkmcnt(0)
	s_waitcnt vmcnt(0)
	s_barrier
	ds_read_b128 v[220:223], v253
	v_mfma_f32_16x16x32_bf16 v[44:47], v[240:243], v[134:137], v[44:47]
	v_mfma_f32_16x16x32_bf16 v[28:31], v[244:247], v[134:137], v[28:31]
	v_mfma_f32_16x16x32_bf16 v[12:15], v[248:251], v[134:137], v[12:15]
	ds_read_b128 v[134:137], v252 offset:32768
	v_mfma_f32_16x16x32_bf16 v[40:43], v[240:243], v[138:141], v[40:43]
	v_mfma_f32_16x16x32_bf16 v[24:27], v[244:247], v[138:141], v[24:27]
	v_mfma_f32_16x16x32_bf16 v[8:11], v[248:251], v[138:141], v[8:11]
	ds_read_b128 v[138:141], v252 offset:34816
	v_mfma_f32_16x16x32_bf16 v[36:39], v[240:243], v[142:145], v[36:39]
	v_mfma_f32_16x16x32_bf16 v[20:23], v[244:247], v[142:145], v[20:23]
	v_mfma_f32_16x16x32_bf16 v[4:7], v[248:251], v[142:145], v[4:7]
	ds_read_b128 v[142:145], v252 offset:36864
	v_mfma_f32_16x16x32_bf16 v[32:35], v[240:243], v[146:149], v[32:35]
	v_mfma_f32_16x16x32_bf16 v[16:19], v[244:247], v[146:149], v[16:19]
	v_mfma_f32_16x16x32_bf16 v[0:3], v[248:251], v[146:149], v[0:3]
	ds_read_b128 v[146:149], v252 offset:38912
	ds_read_b128 v[224:227], v253 offset:2048
	ds_read_b128 v[228:231], v253 offset:4096
	ds_read_b128 v[232:235], v253 offset:6144
	v_mov_b32_e32 v150, v253
	s_branch .Lmy_xf_168
.Lmy_xexit_168:
	s_setprio 0
	s_waitcnt lgkmcnt(2)
	v_mfma_f32_16x16x32_bf16 v[44:47], v[240:243], v[134:137], v[44:47]
	v_mfma_f32_16x16x32_bf16 v[40:43], v[240:243], v[138:141], v[40:43]
	v_mfma_f32_16x16x32_bf16 v[36:39], v[240:243], v[142:145], v[36:39]
	v_mfma_f32_16x16x32_bf16 v[32:35], v[240:243], v[146:149], v[32:35]
	s_waitcnt lgkmcnt(1)
	v_mfma_f32_16x16x32_bf16 v[28:31], v[244:247], v[134:137], v[28:31]
	v_mfma_f32_16x16x32_bf16 v[24:27], v[244:247], v[138:141], v[24:27]
	v_mfma_f32_16x16x32_bf16 v[20:23], v[244:247], v[142:145], v[20:23]
	v_mfma_f32_16x16x32_bf16 v[16:19], v[244:247], v[146:149], v[16:19]
	s_waitcnt lgkmcnt(0)
	v_mfma_f32_16x16x32_bf16 v[12:15], v[248:251], v[134:137], v[12:15]
	v_mfma_f32_16x16x32_bf16 v[8:11], v[248:251], v[138:141], v[8:11]
	v_mfma_f32_16x16x32_bf16 v[4:7], v[248:251], v[142:145], v[4:7]
	v_mfma_f32_16x16x32_bf16 v[0:3], v[248:251], v[146:149], v[0:3]
	s_waitcnt vmcnt(0)
	s_barrier
	s_branch .LBB0_186

; DEVI f32x4 mfma16(bf16x8 a, bf16x8 b, f32x4 c) { return __builtin_amdgcn_mfma_f32_16x16x32_bf16(a, b, c, 0, 0, 0); }
; template <int MODE, class Epi>
; DEVI void gemm256_phase(int sw, const bf16_t* __restrict__ W, int ldw, const bf16_t* __restrict__ X, int ldx, int K, int nN, char* shm, const Epi& epi) {
;     ...
; #pragma unroll
;       for (int ks = 0; ks < 2; ++ks) {
;         const int kx = (wid >> 2) ? (1 - 2 * ks) * 1024 : 0;
;         bf16x8 At[8], Bf[4];
; #pragma unroll
;         for (int m = 0; m < 8; ++m) At[m] = *(const bf16x8*)(SAp + (2 * m + ks) * 1024 + kx);
; #pragma unroll
;         for (int n = 0; n < 4; ++n) Bf[n] = *(const bf16x8*)(SBp + (2 * n + ks) * 1024 + kx);
; #pragma unroll
;         for (int m = 0; m < 8; ++m)
; #pragma unroll
;           for (int n = 0; n < 4; ++n) acc[m][n] = mfma16(At[m], Bf[n], acc[m][n]);
;         __builtin_amdgcn_sched_barrier(0);
;         if (ks == 0 && wid >= 4) {
;           if (st_own) stage(cur ^ 1, n0, m0, kt0 + t + 1);
;           else if (st_next) stage(cur ^ 1, n1, m1, kt1);
;         }
;       }
;       asm volatile("s_waitcnt vmcnt(0)" ::: "memory");
;       __syncthreads();
.LBB0_703:
.Lmy_xs_704:
	s_waitcnt lgkmcnt(2)
	v_mfma_f32_16x16x32_bf16 v[124:127], v[220:223], v[134:137], v[124:127]
	v_mfma_f32_16x16x32_bf16 v[120:123], v[220:223], v[142:145], v[120:123]
	v_mfma_f32_16x16x32_bf16 v[116:119], v[220:223], v[146:149], v[116:119]
	v_mfma_f32_16x16x32_bf16 v[112:115], v[220:223], v[150:153], v[112:115]
	ds_read_b128 v[236:239], v154 offset:9216
	s_waitcnt lgkmcnt(3)
	v_mfma_f32_16x16x32_bf16 v[108:111], v[224:227], v[134:137], v[108:111]
	v_mfma_f32_16x16x32_bf16 v[104:107], v[224:227], v[142:145], v[104:107]
	v_mfma_f32_16x16x32_bf16 v[100:103], v[224:227], v[146:149], v[100:103]
	v_mfma_f32_16x16x32_bf16 v[96:99], v[224:227], v[150:153], v[96:99]
	ds_read_b128 v[240:243], v154 offset:11264
	s_waitcnt lgkmcnt(3)
	v_mfma_f32_16x16x32_bf16 v[92:95], v[228:231], v[134:137], v[92:95]
	v_mfma_f32_16x16x32_bf16 v[88:91], v[228:231], v[142:145], v[88:91]
	v_mfma_f32_16x16x32_bf16 v[84:87], v[228:231], v[146:149], v[84:87]
	v_mfma_f32_16x16x32_bf16 v[80:83], v[228:231], v[150:153], v[80:83]
	ds_read_b128 v[244:247], v154 offset:13312
	s_waitcnt lgkmcnt(3)
	v_mfma_f32_16x16x32_bf16 v[76:79], v[232:235], v[134:137], v[76:79]
	v_mfma_f32_16x16x32_bf16 v[72:75], v[232:235], v[142:145], v[72:75]
	v_mfma_f32_16x16x32_bf16 v[68:71], v[232:235], v[146:149], v[68:71]
	v_mfma_f32_16x16x32_bf16 v[64:67], v[232:235], v[150:153], v[64:67]
	ds_read_b128 v[248:251], v154 offset:15360
	s_waitcnt lgkmcnt(3)
	v_mfma_f32_16x16x32_bf16 v[60:63], v[236:239], v[134:137], v[60:63]
	v_mfma_f32_16x16x32_bf16 v[56:59], v[236:239], v[142:145], v[56:59]
	v_mfma_f32_16x16x32_bf16 v[52:55], v[236:239], v[146:149], v[52:55]
	v_mfma_f32_16x16x32_bf16 v[48:51], v[236:239], v[150:153], v[48:51]
	s_addk_i32 s81, 0x80
	s_cmp_eq_u32 s80, s82
	s_cbranch_scc1 .Lmy_xexit_704
	s_add_i32 s0, s61, s82
	s_and_b32 s83, s0, 1
	s_add_i32 s82, s82, 1
	s_cmp_lt_i32 s82, s54
	s_cselect_b64 s[0:1], -1, 0
	s_cmp_ge_i32 s82, s54
	s_cselect_b64 s[40:41], -1, 0
	v_cmp_ne_u32_e32 vcc, 1, v197
	v_cndmask_b32_e64 v128, 0, 1, s[0:1]
	s_and_b64 s[40:41], s[38:39], s[40:41]
	v_cmp_ne_u32_e64 s[0:1], 1, v128
	s_lshl_b32 s42, s83, 16
	s_add_i32 s43, s42, s58
	v_add_u32_e32 v129, s43, v194
	v_add_u32_e32 v253, s62, v129
	s_or_b32 s43, s42, s59
	v_add_u32_e32 v128, s43, v194
	v_add_u32_e32 v252, s62, v128
	s_waitcnt lgkmcnt(0)
	s_waitcnt vmcnt(0)
	s_barrier
	ds_read_b128 v[220:223], v253
	ds_read_b128 v[138:141], v252 offset:34816
	v_mfma_f32_16x16x32_bf16 v[44:47], v[240:243], v[134:137], v[44:47]
	v_mfma_f32_16x16x32_bf16 v[28:31], v[244:247], v[134:137], v[28:31]
	v_mfma_f32_16x16x32_bf16 v[12:15], v[248:251], v[134:137], v[12:15]
	ds_read_b128 v[134:137], v252 offset:32768
	v_mfma_f32_16x16x32_bf16 v[40:43], v[240:243], v[142:145], v[40:43]
	v_mfma_f32_16x16x32_bf16 v[24:27], v[244:247], v[142:145], v[24:27]
	v_mfma_f32_16x16x32_bf16 v[8:11], v[248:251], v[142:145], v[8:11]
	ds_read_b128 v[142:145], v252 offset:36864
	v_mfma_f32_16x16x32_bf16 v[36:39], v[240:243], v[146:149], v[36:39]
	v_mfma_f32_16x16x32_bf16 v[20:23], v[244:247], v[146:149], v[20:23]
	v_mfma_f32_16x16x32_bf16 v[4:7], v[248:251], v[146:149], v[4:7]
	ds_read_b128 v[146:149], v252 offset:38912
	v_mfma_f32_16x16x32_bf16 v[32:35], v[240:243], v[150:153], v[32:35]
	v_mfma_f32_16x16x32_bf16 v[16:19], v[244:247], v[150:153], v[16:19]
	v_mfma_f32_16x16x32_bf16 v[0:3], v[248:251], v[150:153], v[0:3]
	ds_read_b128 v[224:227], v253 offset:2048
	ds_read_b128 v[228:231], v253 offset:4096
	ds_read_b128 v[232:235], v253 offset:6144
	v_mov_b32_e32 v150, v253
	s_branch .Lmy_xf_704
.Lmy_xexit_704:
	s_setprio 0
	s_waitcnt lgkmcnt(2)
	v_mfma_f32_16x16x32_bf16 v[44:47], v[240:243], v[134:137], v[44:47]
	v_mfma_f32_16x16x32_bf16 v[40:43], v[240:243], v[142:145], v[40:43]
	v_mfma_f32_16x16x32_bf16 v[36:39], v[240:243], v[146:149], v[36:39]
	v_mfma_f32_16x16x32_bf16 v[32:35], v[240:243], v[150:153], v[32:35]
	s_waitcnt lgkmcnt(1)
	v_mfma_f32_16x16x32_bf16 v[28:31], v[244:247], v[134:137], v[28:31]
	v_mfma_f32_16x16x32_bf16 v[24:27], v[244:247], v[142:145], v[24:27]
	v_mfma_f32_16x16x32_bf16 v[20:23], v[244:247], v[146:149], v[20:23]
	v_mfma_f32_16x16x32_bf16 v[16:19], v[244:247], v[150:153], v[16:19]
	s_waitcnt lgkmcnt(0)
	v_mfma_f32_16x16x32_bf16 v[12:15], v[248:251], v[134:137], v[12:15]
	v_mfma_f32_16x16x32_bf16 v[8:11], v[248:251], v[142:145], v[8:11]
	v_mfma_f32_16x16x32_bf16 v[4:7], v[248:251], v[146:149], v[4:7]
	v_mfma_f32_16x16x32_bf16 v[0:3], v[248:251], v[150:153], v[0:3]
	s_waitcnt vmcnt(0)
	s_barrier
	s_branch .LBB0_724

; DEVI f32x4 mfma16(bf16x8 a, bf16x8 b, f32x4 c) { return __builtin_amdgcn_mfma_f32_16x16x32_bf16(a, b, c, 0, 0, 0); }
; template <int MODE, class Epi>
; DEVI void gemm256_phase(int sw, const bf16_t* __restrict__ W, int ldw, const bf16_t* __restrict__ X, int ldx, int K, int nN, char* shm, const Epi& epi) {
;     ...
; #pragma unroll
;       for (int ks = 0; ks < 2; ++ks) {
;         const int kx = (wid >> 2) ? (1 - 2 * ks) * 1024 : 0;
;         bf16x8 At[8], Bf[4];
; #pragma unroll
;         for (int m = 0; m < 8; ++m) At[m] = *(const bf16x8*)(SAp + (2 * m + ks) * 1024 + kx);
; #pragma unroll
;         for (int n = 0; n < 4; ++n) Bf[n] = *(const bf16x8*)(SBp + (2 * n + ks) * 1024 + kx);
; #pragma unroll
;         for (int m = 0; m < 8; ++m)
; #pragma unroll
;           for (int n = 0; n < 4; ++n) acc[m][n] = mfma16(At[m], Bf[n], acc[m][n]);
;         __builtin_amdgcn_sched_barrier(0);
;         if (ks == 0 && wid >= 4) {
;           if (st_own) stage(cur ^ 1, n0, m0, kt0 + t + 1);
;           else if (st_next) stage(cur ^ 1, n1, m1, kt1);
;         }
;       }
;       asm volatile("s_waitcnt vmcnt(0)" ::: "memory");
;       __syncthreads();
.LBB0_984:
.Lmy_xs_985:
	s_waitcnt lgkmcnt(2)
	v_mfma_f32_16x16x32_bf16 v[124:127], v[220:223], v[134:137], v[124:127]
	v_mfma_f32_16x16x32_bf16 v[120:123], v[220:223], v[142:145], v[120:123]
	v_mfma_f32_16x16x32_bf16 v[116:119], v[220:223], v[146:149], v[116:119]
	v_mfma_f32_16x16x32_bf16 v[112:115], v[220:223], v[150:153], v[112:115]
	ds_read_b128 v[236:239], v154 offset:9216
	s_waitcnt lgkmcnt(3)
	v_mfma_f32_16x16x32_bf16 v[108:111], v[224:227], v[134:137], v[108:111]
	v_mfma_f32_16x16x32_bf16 v[104:107], v[224:227], v[142:145], v[104:107]
	v_mfma_f32_16x16x32_bf16 v[100:103], v[224:227], v[146:149], v[100:103]
	v_mfma_f32_16x16x32_bf16 v[96:99], v[224:227], v[150:153], v[96:99]
	ds_read_b128 v[240:243], v154 offset:11264
	s_waitcnt lgkmcnt(3)
	v_mfma_f32_16x16x32_bf16 v[92:95], v[228:231], v[134:137], v[92:95]
	v_mfma_f32_16x16x32_bf16 v[88:91], v[228:231], v[142:145], v[88:91]
	v_mfma_f32_16x16x32_bf16 v[84:87], v[228:231], v[146:149], v[84:87]
	v_mfma_f32_16x16x32_bf16 v[80:83], v[228:231], v[150:153], v[80:83]
	ds_read_b128 v[244:247], v154 offset:13312
	s_waitcnt lgkmcnt(3)
	v_mfma_f32_16x16x32_bf16 v[76:79], v[232:235], v[134:137], v[76:79]
	v_mfma_f32_16x16x32_bf16 v[72:75], v[232:235], v[142:145], v[72:75]
	v_mfma_f32_16x16x32_bf16 v[68:71], v[232:235], v[146:149], v[68:71]
	v_mfma_f32_16x16x32_bf16 v[64:67], v[232:235], v[150:153], v[64:67]
	ds_read_b128 v[248:251], v154 offset:15360
	s_waitcnt lgkmcnt(3)
	v_mfma_f32_16x16x32_bf16 v[60:63], v[236:239], v[134:137], v[60:63]
	v_mfma_f32_16x16x32_bf16 v[56:59], v[236:239], v[142:145], v[56:59]
	v_mfma_f32_16x16x32_bf16 v[52:55], v[236:239], v[146:149], v[52:55]
	v_mfma_f32_16x16x32_bf16 v[48:51], v[236:239], v[150:153], v[48:51]
	s_addk_i32 s57, 0x80
	s_cmp_eq_u32 s54, s58
	s_cbranch_scc1 .Lmy_xexit_985
	s_add_i32 s10, s37, s58
	s_and_b32 s60, s10, 1
	s_mov_b64 s[10:11], -1
	s_and_b64 vcc, exec, s[4:5]
	s_lshl_b32 s59, s60, 16
	s_add_i32 s10, s59, s38
	v_add_u32_e32 v129, s10, v198
	v_add_u32_e32 v253, s41, v129
	s_add_i32 s10, s59, s39
	v_add_u32_e32 v128, s10, v198
	v_add_u32_e32 v252, s41, v128
	s_waitcnt lgkmcnt(0)
	s_waitcnt vmcnt(0)
	s_barrier
	ds_read_b128 v[220:223], v253
	ds_read_b128 v[224:227], v253 offset:2048
	v_mfma_f32_16x16x32_bf16 v[44:47], v[240:243], v[134:137], v[44:47]
	v_mfma_f32_16x16x32_bf16 v[28:31], v[244:247], v[134:137], v[28:31]
	v_mfma_f32_16x16x32_bf16 v[12:15], v[248:251], v[134:137], v[12:15]
	ds_read_b128 v[134:137], v252 offset:32768
	v_mfma_f32_16x16x32_bf16 v[40:43], v[240:243], v[142:145], v[40:43]
	v_mfma_f32_16x16x32_bf16 v[24:27], v[244:247], v[142:145], v[24:27]
	v_mfma_f32_16x16x32_bf16 v[8:11], v[248:251], v[142:145], v[8:11]
	ds_read_b128 v[142:145], v252 offset:34816
	v_mfma_f32_16x16x32_bf16 v[36:39], v[240:243], v[146:149], v[36:39]
	v_mfma_f32_16x16x32_bf16 v[20:23], v[244:247], v[146:149], v[20:23]
	v_mfma_f32_16x16x32_bf16 v[4:7], v[248:251], v[146:149], v[4:7]
	ds_read_b128 v[146:149], v252 offset:36864
	v_mfma_f32_16x16x32_bf16 v[32:35], v[240:243], v[150:153], v[32:35]
	v_mfma_f32_16x16x32_bf16 v[16:19], v[244:247], v[150:153], v[16:19]
	v_mfma_f32_16x16x32_bf16 v[0:3], v[248:251], v[150:153], v[0:3]
	ds_read_b128 v[150:153], v252 offset:38912
	ds_read_b128 v[228:231], v253 offset:4096
	ds_read_b128 v[232:235], v253 offset:6144
	v_mov_b32_e32 v154, v253
	s_branch .Lmy_xf_985

; DEVI f32x4 mfma16(bf16x8 a, bf16x8 b, f32x4 c) { return __builtin_amdgcn_mfma_f32_16x16x32_bf16(a, b, c, 0, 0, 0); }
; template <int MODE, class Epi>
; DEVI void gemm256_phase(int sw, const bf16_t* __restrict__ W, int ldw, const bf16_t* __restrict__ X, int ldx, int K, int nN, char* shm, const Epi& epi) {
;     ...
; #pragma unroll
;       for (int ks = 0; ks < 2; ++ks) {
;         const int kx = (wid >> 2) ? (1 - 2 * ks) * 1024 : 0;
;         bf16x8 At[8], Bf[4];
; #pragma unroll
;         for (int m = 0; m < 8; ++m) At[m] = *(const bf16x8*)(SAp + (2 * m + ks) * 1024 + kx);
; #pragma unroll
;         for (int n = 0; n < 4; ++n) Bf[n] = *(const bf16x8*)(SBp + (2 * n + ks) * 1024 + kx);
; #pragma unroll
;         for (int m = 0; m < 8; ++m)
; #pragma unroll
;           for (int n = 0; n < 4; ++n) acc[m][n] = mfma16(At[m], Bf[n], acc[m][n]);
;         __builtin_amdgcn_sched_barrier(0);
;         if (ks == 0 && wid >= 4) {
;           if (st_own) stage(cur ^ 1, n0, m0, kt0 + t + 1);
;           else if (st_next) stage(cur ^ 1, n1, m1, kt1);
;         }
;       }
;       asm volatile("s_waitcnt vmcnt(0)" ::: "memory");
;       __syncthreads();
.LBB0_1033:
.Lmy_xs_1034:
	s_waitcnt lgkmcnt(2)
	v_mfma_f32_16x16x32_bf16 v[124:127], v[220:223], v[134:137], v[124:127]
	v_mfma_f32_16x16x32_bf16 v[120:123], v[220:223], v[142:145], v[120:123]
	v_mfma_f32_16x16x32_bf16 v[116:119], v[220:223], v[146:149], v[116:119]
	v_mfma_f32_16x16x32_bf16 v[112:115], v[220:223], v[150:153], v[112:115]
	ds_read_b128 v[236:239], v154 offset:9216
	s_waitcnt lgkmcnt(3)
	v_mfma_f32_16x16x32_bf16 v[108:111], v[224:227], v[134:137], v[108:111]
	v_mfma_f32_16x16x32_bf16 v[104:107], v[224:227], v[142:145], v[104:107]
	v_mfma_f32_16x16x32_bf16 v[100:103], v[224:227], v[146:149], v[100:103]
	v_mfma_f32_16x16x32_bf16 v[96:99], v[224:227], v[150:153], v[96:99]
	ds_read_b128 v[240:243], v154 offset:11264
	s_waitcnt lgkmcnt(3)
	v_mfma_f32_16x16x32_bf16 v[92:95], v[228:231], v[134:137], v[92:95]
	v_mfma_f32_16x16x32_bf16 v[88:91], v[228:231], v[142:145], v[88:91]
	v_mfma_f32_16x16x32_bf16 v[84:87], v[228:231], v[146:149], v[84:87]
	v_mfma_f32_16x16x32_bf16 v[80:83], v[228:231], v[150:153], v[80:83]
	ds_read_b128 v[244:247], v154 offset:13312
	s_waitcnt lgkmcnt(3)
	v_mfma_f32_16x16x32_bf16 v[76:79], v[232:235], v[134:137], v[76:79]
	v_mfma_f32_16x16x32_bf16 v[72:75], v[232:235], v[142:145], v[72:75]
	v_mfma_f32_16x16x32_bf16 v[68:71], v[232:235], v[146:149], v[68:71]
	v_mfma_f32_16x16x32_bf16 v[64:67], v[232:235], v[150:153], v[64:67]
	ds_read_b128 v[248:251], v154 offset:15360
	s_waitcnt lgkmcnt(3)
	v_mfma_f32_16x16x32_bf16 v[60:63], v[236:239], v[134:137], v[60:63]
	v_mfma_f32_16x16x32_bf16 v[56:59], v[236:239], v[142:145], v[56:59]
	v_mfma_f32_16x16x32_bf16 v[52:55], v[236:239], v[146:149], v[52:55]
	v_mfma_f32_16x16x32_bf16 v[48:51], v[236:239], v[150:153], v[48:51]
	s_addk_i32 s81, 0x80
	s_cmp_eq_u32 s80, s82
	s_cbranch_scc1 .Lmy_xexit_1034
	s_add_i32 s0, s61, s82
	s_and_b32 s83, s0, 1
	s_add_i32 s82, s82, 1
	s_cmp_lt_i32 s82, s54
	s_cselect_b64 s[0:1], -1, 0
	s_cmp_ge_i32 s82, s54
	s_cselect_b64 s[40:41], -1, 0
	v_cmp_ne_u32_e32 vcc, 1, v197
	v_cndmask_b32_e64 v128, 0, 1, s[0:1]
	s_and_b64 s[40:41], s[38:39], s[40:41]
	v_cmp_ne_u32_e64 s[0:1], 1, v128
	s_lshl_b32 s42, s83, 16
	s_add_i32 s43, s42, s58
	v_add_u32_e32 v129, s43, v194
	v_add_u32_e32 v253, s62, v129
	s_or_b32 s43, s42, s59
	v_add_u32_e32 v128, s43, v194
	v_add_u32_e32 v252, s62, v128
	s_waitcnt lgkmcnt(0)
	s_waitcnt vmcnt(0)
	s_barrier
	ds_read_b128 v[220:223], v253
	ds_read_b128 v[224:227], v253 offset:2048
	v_mfma_f32_16x16x32_bf16 v[44:47], v[240:243], v[134:137], v[44:47]
	v_mfma_f32_16x16x32_bf16 v[28:31], v[244:247], v[134:137], v[28:31]
	v_mfma_f32_16x16x32_bf16 v[12:15], v[248:251], v[134:137], v[12:15]
	ds_read_b128 v[134:137], v252 offset:32768
	v_mfma_f32_16x16x32_bf16 v[40:43], v[240:243], v[142:145], v[40:43]
	v_mfma_f32_16x16x32_bf16 v[24:27], v[244:247], v[142:145], v[24:27]
	v_mfma_f32_16x16x32_bf16 v[8:11], v[248:251], v[142:145], v[8:11]
	ds_read_b128 v[142:145], v252 offset:34816
	v_mfma_f32_16x16x32_bf16 v[36:39], v[240:243], v[146:149], v[36:39]
	v_mfma_f32_16x16x32_bf16 v[20:23], v[244:247], v[146:149], v[20:23]
	v_mfma_f32_16x16x32_bf16 v[4:7], v[248:251], v[146:149], v[4:7]
	ds_read_b128 v[146:149], v252 offset:36864
	v_mfma_f32_16x16x32_bf16 v[32:35], v[240:243], v[150:153], v[32:35]
	v_mfma_f32_16x16x32_bf16 v[16:19], v[244:247], v[150:153], v[16:19]
	v_mfma_f32_16x16x32_bf16 v[0:3], v[248:251], v[150:153], v[0:3]
	ds_read_b128 v[150:153], v252 offset:38912
	ds_read_b128 v[228:231], v253 offset:4096
	ds_read_b128 v[232:235], v253 offset:6144
	v_mov_b32_e32 v154, v253
	s_branch .Lmy_xf_1034

; DEVI f32x4 mfma16(bf16x8 a, bf16x8 b, f32x4 c) { return __builtin_amdgcn_mfma_f32_16x16x32_bf16(a, b, c, 0, 0, 0); }
; template <int MODE, class Epi>
; DEVI void gemm256_phase(int sw, const bf16_t* __restrict__ W, int ldw, const bf16_t* __restrict__ X, int ldx, int K, int nN, char* shm, const Epi& epi) {
;     ...
; #pragma unroll
;       for (int ks = 0; ks < 2; ++ks) {
;         const int kx = (wid >> 2) ? (1 - 2 * ks) * 1024 : 0;
;         bf16x8 At[8], Bf[4];
; #pragma unroll
;         for (int m = 0; m < 8; ++m) At[m] = *(const bf16x8*)(SAp + (2 * m + ks) * 1024 + kx);
; #pragma unroll
;         for (int n = 0; n < 4; ++n) Bf[n] = *(const bf16x8*)(SBp + (2 * n + ks) * 1024 + kx);
; #pragma unroll
;         for (int m = 0; m < 8; ++m)
; #pragma unroll
;           for (int n = 0; n < 4; ++n) acc[m][n] = mfma16(At[m], Bf[n], acc[m][n]);
;         __builtin_amdgcn_sched_barrier(0);
;         if (ks == 0 && wid >= 4) {
;           if (st_own) stage(cur ^ 1, n0, m0, kt0 + t + 1);
;           else if (st_next) stage(cur ^ 1, n1, m1, kt1);
;         }
;       }
;       asm volatile("s_waitcnt vmcnt(0)" ::: "memory");
;       __syncthreads();
.LBB0_1269:
.Lmy_xs_1270:
	s_waitcnt lgkmcnt(2)
	v_mfma_f32_16x16x32_bf16 v[124:127], v[220:223], v[134:137], v[124:127]
	v_mfma_f32_16x16x32_bf16 v[120:123], v[220:223], v[142:145], v[120:123]
	v_mfma_f32_16x16x32_bf16 v[116:119], v[220:223], v[146:149], v[116:119]
	v_mfma_f32_16x16x32_bf16 v[112:115], v[220:223], v[150:153], v[112:115]
	ds_read_b128 v[236:239], v154 offset:9216
	s_waitcnt lgkmcnt(3)
	v_mfma_f32_16x16x32_bf16 v[108:111], v[224:227], v[134:137], v[108:111]
	v_mfma_f32_16x16x32_bf16 v[104:107], v[224:227], v[142:145], v[104:107]
	v_mfma_f32_16x16x32_bf16 v[100:103], v[224:227], v[146:149], v[100:103]
	v_mfma_f32_16x16x32_bf16 v[96:99], v[224:227], v[150:153], v[96:99]
	ds_read_b128 v[240:243], v154 offset:11264
	s_waitcnt lgkmcnt(3)
	v_mfma_f32_16x16x32_bf16 v[92:95], v[228:231], v[134:137], v[92:95]
	v_mfma_f32_16x16x32_bf16 v[88:91], v[228:231], v[142:145], v[88:91]
	v_mfma_f32_16x16x32_bf16 v[84:87], v[228:231], v[146:149], v[84:87]
	v_mfma_f32_16x16x32_bf16 v[80:83], v[228:231], v[150:153], v[80:83]
	ds_read_b128 v[244:247], v154 offset:13312
	s_waitcnt lgkmcnt(3)
	v_mfma_f32_16x16x32_bf16 v[76:79], v[232:235], v[134:137], v[76:79]
	v_mfma_f32_16x16x32_bf16 v[72:75], v[232:235], v[142:145], v[72:75]
	v_mfma_f32_16x16x32_bf16 v[68:71], v[232:235], v[146:149], v[68:71]
	v_mfma_f32_16x16x32_bf16 v[64:67], v[232:235], v[150:153], v[64:67]
	ds_read_b128 v[248:251], v154 offset:15360
	s_waitcnt lgkmcnt(3)
	v_mfma_f32_16x16x32_bf16 v[60:63], v[236:239], v[134:137], v[60:63]
	v_mfma_f32_16x16x32_bf16 v[56:59], v[236:239], v[142:145], v[56:59]
	v_mfma_f32_16x16x32_bf16 v[52:55], v[236:239], v[146:149], v[52:55]
	v_mfma_f32_16x16x32_bf16 v[48:51], v[236:239], v[150:153], v[48:51]
	s_addk_i32 s72, 0x80
	s_cmp_eq_u32 s71, s73
	s_cbranch_scc1 .Lmy_xexit_1270
	s_add_i32 s0, s49, s73
	s_and_b32 s74, s0, 1
	s_add_i32 s73, s73, 1
	s_cmp_lt_i32 s73, s54
	s_cselect_b64 s[0:1], -1, 0
	s_cmp_ge_i32 s73, s54
	s_cselect_b64 s[8:9], -1, 0
	v_cndmask_b32_e64 v128, 0, 1, s[0:1]
	s_and_b64 s[8:9], s[2:3], s[8:9]
	s_andn2_b64 vcc, exec, s[40:41]
	v_cmp_ne_u32_e64 s[0:1], 1, v128
	s_lshl_b32 s10, s74, 16
	s_add_i32 s11, s10, s55
	v_add_u32_e32 v129, s11, v194
	v_add_u32_e32 v253, s57, v129
	s_or_b32 s11, s10, s56
	v_add_u32_e32 v128, s11, v194
	v_add_u32_e32 v252, s57, v128
	s_waitcnt lgkmcnt(0)
	s_waitcnt vmcnt(0)
	s_barrier
	ds_read_b128 v[220:223], v253
	ds_read_b128 v[224:227], v253 offset:2048
	v_mfma_f32_16x16x32_bf16 v[44:47], v[240:243], v[134:137], v[44:47]
	v_mfma_f32_16x16x32_bf16 v[28:31], v[244:247], v[134:137], v[28:31]
	v_mfma_f32_16x16x32_bf16 v[12:15], v[248:251], v[134:137], v[12:15]
	ds_read_b128 v[134:137], v252 offset:32768
	v_mfma_f32_16x16x32_bf16 v[40:43], v[240:243], v[142:145], v[40:43]
	v_mfma_f32_16x16x32_bf16 v[24:27], v[244:247], v[142:145], v[24:27]
	v_mfma_f32_16x16x32_bf16 v[8:11], v[248:251], v[142:145], v[8:11]
	ds_read_b128 v[142:145], v252 offset:34816
	v_mfma_f32_16x16x32_bf16 v[36:39], v[240:243], v[146:149], v[36:39]
	v_mfma_f32_16x16x32_bf16 v[20:23], v[244:247], v[146:149], v[20:23]
	v_mfma_f32_16x16x32_bf16 v[4:7], v[248:251], v[146:149], v[4:7]
	ds_read_b128 v[146:149], v252 offset:36864
	v_mfma_f32_16x16x32_bf16 v[32:35], v[240:243], v[150:153], v[32:35]
	v_mfma_f32_16x16x32_bf16 v[16:19], v[244:247], v[150:153], v[16:19]
	v_mfma_f32_16x16x32_bf16 v[0:3], v[248:251], v[150:153], v[0:3]
	ds_read_b128 v[150:153], v252 offset:38912
	ds_read_b128 v[228:231], v253 offset:4096
	ds_read_b128 v[232:235], v253 offset:6144
	v_mov_b32_e32 v154, v253
	s_branch .Lmy_xf_1270

; DEVI f32x4 mfma16(bf16x8 a, bf16x8 b, f32x4 c) { return __builtin_amdgcn_mfma_f32_16x16x32_bf16(a, b, c, 0, 0, 0); }
; template <int MODE, class Epi>
; DEVI void gemm256_phase(int sw, const bf16_t* __restrict__ W, int ldw, const bf16_t* __restrict__ X, int ldx, int K, int nN, char* shm, const Epi& epi) {
;     ...
; #pragma unroll
;       for (int ks = 0; ks < 2; ++ks) {
;         const int kx = (wid >> 2) ? (1 - 2 * ks) * 1024 : 0;
;         bf16x8 At[8], Bf[4];
; #pragma unroll
;         for (int m = 0; m < 8; ++m) At[m] = *(const bf16x8*)(SAp + (2 * m + ks) * 1024 + kx);
; #pragma unroll
;         for (int n = 0; n < 4; ++n) Bf[n] = *(const bf16x8*)(SBp + (2 * n + ks) * 1024 + kx);
; #pragma unroll
;         for (int m = 0; m < 8; ++m)
; #pragma unroll
;           for (int n = 0; n < 4; ++n) acc[m][n] = mfma16(At[m], Bf[n], acc[m][n]);
;         __builtin_amdgcn_sched_barrier(0);
;         if (ks == 0 && wid >= 4) {
;           if (st_own) stage(cur ^ 1, n0, m0, kt0 + t + 1);
;           else if (st_next) stage(cur ^ 1, n1, m1, kt1);
;         }
;       }
;       asm volatile("s_waitcnt vmcnt(0)" ::: "memory");
;       __syncthreads();
.LBB0_1677:
.Lmy_xs_1678:
	s_waitcnt lgkmcnt(2)
	v_mfma_f32_16x16x32_bf16 v[124:127], v[220:223], v[134:137], v[124:127]
	v_mfma_f32_16x16x32_bf16 v[120:123], v[220:223], v[142:145], v[120:123]
	v_mfma_f32_16x16x32_bf16 v[116:119], v[220:223], v[146:149], v[116:119]
	v_mfma_f32_16x16x32_bf16 v[112:115], v[220:223], v[150:153], v[112:115]
	ds_read_b128 v[236:239], v154 offset:9216
	s_waitcnt lgkmcnt(3)
	v_mfma_f32_16x16x32_bf16 v[108:111], v[224:227], v[134:137], v[108:111]
	v_mfma_f32_16x16x32_bf16 v[104:107], v[224:227], v[142:145], v[104:107]
	v_mfma_f32_16x16x32_bf16 v[100:103], v[224:227], v[146:149], v[100:103]
	v_mfma_f32_16x16x32_bf16 v[96:99], v[224:227], v[150:153], v[96:99]
	ds_read_b128 v[240:243], v154 offset:11264
	s_waitcnt lgkmcnt(3)
	v_mfma_f32_16x16x32_bf16 v[92:95], v[228:231], v[134:137], v[92:95]
	v_mfma_f32_16x16x32_bf16 v[88:91], v[228:231], v[142:145], v[88:91]
	v_mfma_f32_16x16x32_bf16 v[84:87], v[228:231], v[146:149], v[84:87]
	v_mfma_f32_16x16x32_bf16 v[80:83], v[228:231], v[150:153], v[80:83]
	ds_read_b128 v[244:247], v154 offset:13312
	s_waitcnt lgkmcnt(3)
	v_mfma_f32_16x16x32_bf16 v[76:79], v[232:235], v[134:137], v[76:79]
	v_mfma_f32_16x16x32_bf16 v[72:75], v[232:235], v[142:145], v[72:75]
	v_mfma_f32_16x16x32_bf16 v[68:71], v[232:235], v[146:149], v[68:71]
	v_mfma_f32_16x16x32_bf16 v[64:67], v[232:235], v[150:153], v[64:67]
	ds_read_b128 v[248:251], v154 offset:15360
	s_waitcnt lgkmcnt(3)
	v_mfma_f32_16x16x32_bf16 v[60:63], v[236:239], v[134:137], v[60:63]
	v_mfma_f32_16x16x32_bf16 v[56:59], v[236:239], v[142:145], v[56:59]
	v_mfma_f32_16x16x32_bf16 v[52:55], v[236:239], v[146:149], v[52:55]
	v_mfma_f32_16x16x32_bf16 v[48:51], v[236:239], v[150:153], v[48:51]
	s_addk_i32 s78, 0x80
	s_cmp_eq_u32 s77, s79
	s_cbranch_scc1 .Lmy_xexit_1678
	s_add_i32 s2, s61, s79
	s_and_b32 s80, s2, 1
	s_add_i32 s79, s79, 1
	s_cmp_lt_i32 s79, s60
	s_cselect_b64 s[2:3], -1, 0
	s_cmp_ge_i32 s79, s60
	s_cselect_b64 s[40:41], -1, 0
	v_cndmask_b32_e64 v128, 0, 1, s[2:3]
	s_and_b64 s[40:41], s[34:35], s[40:41]
	s_and_b64 vcc, exec, s[0:1]
	v_cmp_ne_u32_e64 s[2:3], 1, v128
	s_lshl_b32 s42, s80, 16
	s_add_i32 s16, s42, s57
	v_add_u32_e32 v129, s16, v194
	v_add_u32_e32 v253, s62, v129
	s_or_b32 s16, s42, s58
	v_add_u32_e32 v128, s16, v194
	v_add_u32_e32 v252, s62, v128
	s_waitcnt lgkmcnt(0)
	s_waitcnt vmcnt(0)
	s_barrier
	ds_read_b128 v[220:223], v253
	ds_read_b128 v[224:227], v253 offset:2048
	v_mfma_f32_16x16x32_bf16 v[44:47], v[240:243], v[134:137], v[44:47]
	v_mfma_f32_16x16x32_bf16 v[28:31], v[244:247], v[134:137], v[28:31]
	v_mfma_f32_16x16x32_bf16 v[12:15], v[248:251], v[134:137], v[12:15]
	ds_read_b128 v[134:137], v252 offset:32768
	v_mfma_f32_16x16x32_bf16 v[40:43], v[240:243], v[142:145], v[40:43]
	v_mfma_f32_16x16x32_bf16 v[24:27], v[244:247], v[142:145], v[24:27]
	v_mfma_f32_16x16x32_bf16 v[8:11], v[248:251], v[142:145], v[8:11]
	ds_read_b128 v[142:145], v252 offset:34816
	v_mfma_f32_16x16x32_bf16 v[36:39], v[240:243], v[146:149], v[36:39]
	v_mfma_f32_16x16x32_bf16 v[20:23], v[244:247], v[146:149], v[20:23]
	v_mfma_f32_16x16x32_bf16 v[4:7], v[248:251], v[146:149], v[4:7]
	ds_read_b128 v[146:149], v252 offset:36864
	v_mfma_f32_16x16x32_bf16 v[32:35], v[240:243], v[150:153], v[32:35]
	v_mfma_f32_16x16x32_bf16 v[16:19], v[244:247], v[150:153], v[16:19]
	v_mfma_f32_16x16x32_bf16 v[0:3], v[248:251], v[150:153], v[0:3]
	ds_read_b128 v[150:153], v252 offset:38912
	ds_read_b128 v[228:231], v253 offset:4096
	ds_read_b128 v[232:235], v253 offset:6144
	v_mov_b32_e32 v154, v253
	s_branch .Lmy_xf_1678

; DEVI f32x4 mfma16(bf16x8 a, bf16x8 b, f32x4 c) { return __builtin_amdgcn_mfma_f32_16x16x32_bf16(a, b, c, 0, 0, 0); }
; template <int MODE, class Epi>
; DEVI void gemm256_phase(int sw, const bf16_t* __restrict__ W, int ldw, const bf16_t* __restrict__ X, int ldx, int K, int nN, char* shm, const Epi& epi) {
;     ...
; #pragma unroll
;       for (int ks = 0; ks < 2; ++ks) {
;         const int kx = (wid >> 2) ? (1 - 2 * ks) * 1024 : 0;
;         bf16x8 At[8], Bf[4];
; #pragma unroll
;         for (int m = 0; m < 8; ++m) At[m] = *(const bf16x8*)(SAp + (2 * m + ks) * 1024 + kx);
; #pragma unroll
;         for (int n = 0; n < 4; ++n) Bf[n] = *(const bf16x8*)(SBp + (2 * n + ks) * 1024 + kx);
; #pragma unroll
;         for (int m = 0; m < 8; ++m)
; #pragma unroll
;           for (int n = 0; n < 4; ++n) acc[m][n] = mfma16(At[m], Bf[n], acc[m][n]);
;         __builtin_amdgcn_sched_barrier(0);
;         if (ks == 0 && wid >= 4) {
;           if (st_own) stage(cur ^ 1, n0, m0, kt0 + t + 1);
;           else if (st_next) stage(cur ^ 1, n1, m1, kt1);
;         }
;       }
;       asm volatile("s_waitcnt vmcnt(0)" ::: "memory");
;       __syncthreads();
.LBB0_1759:
.Lmy_xs_1760:
	s_waitcnt lgkmcnt(2)
	v_mfma_f32_16x16x32_bf16 v[124:127], v[220:223], v[134:137], v[124:127]
	v_mfma_f32_16x16x32_bf16 v[120:123], v[220:223], v[142:145], v[120:123]
	v_mfma_f32_16x16x32_bf16 v[116:119], v[220:223], v[146:149], v[116:119]
	v_mfma_f32_16x16x32_bf16 v[112:115], v[220:223], v[150:153], v[112:115]
	ds_read_b128 v[236:239], v154 offset:9216
	s_waitcnt lgkmcnt(3)
	v_mfma_f32_16x16x32_bf16 v[108:111], v[224:227], v[134:137], v[108:111]
	v_mfma_f32_16x16x32_bf16 v[104:107], v[224:227], v[142:145], v[104:107]
	v_mfma_f32_16x16x32_bf16 v[100:103], v[224:227], v[146:149], v[100:103]
	v_mfma_f32_16x16x32_bf16 v[96:99], v[224:227], v[150:153], v[96:99]
	ds_read_b128 v[240:243], v154 offset:11264
	s_waitcnt lgkmcnt(3)
	v_mfma_f32_16x16x32_bf16 v[92:95], v[228:231], v[134:137], v[92:95]
	v_mfma_f32_16x16x32_bf16 v[88:91], v[228:231], v[142:145], v[88:91]
	v_mfma_f32_16x16x32_bf16 v[84:87], v[228:231], v[146:149], v[84:87]
	v_mfma_f32_16x16x32_bf16 v[80:83], v[228:231], v[150:153], v[80:83]
	ds_read_b128 v[244:247], v154 offset:13312
	s_waitcnt lgkmcnt(3)
	v_mfma_f32_16x16x32_bf16 v[76:79], v[232:235], v[134:137], v[76:79]
	v_mfma_f32_16x16x32_bf16 v[72:75], v[232:235], v[142:145], v[72:75]
	v_mfma_f32_16x16x32_bf16 v[68:71], v[232:235], v[146:149], v[68:71]
	v_mfma_f32_16x16x32_bf16 v[64:67], v[232:235], v[150:153], v[64:67]
	ds_read_b128 v[248:251], v154 offset:15360
	s_waitcnt lgkmcnt(3)
	v_mfma_f32_16x16x32_bf16 v[60:63], v[236:239], v[134:137], v[60:63]
	v_mfma_f32_16x16x32_bf16 v[56:59], v[236:239], v[142:145], v[56:59]
	v_mfma_f32_16x16x32_bf16 v[52:55], v[236:239], v[146:149], v[52:55]
	v_mfma_f32_16x16x32_bf16 v[48:51], v[236:239], v[150:153], v[48:51]
	s_addk_i32 s49, 0x80
	s_cmp_eq_u32 s46, s50
	s_cbranch_scc1 .Lmy_xexit_1760
	s_add_i32 s10, s31, s50
	s_and_b32 s52, s10, 1
	s_mov_b64 s[10:11], -1
	s_and_b64 vcc, exec, s[4:5]
	s_lshl_b32 s51, s52, 16
	s_add_i32 s10, s51, s34
	v_add_u32_e32 v129, s10, v198
	v_add_u32_e32 v253, s37, v129
	s_add_i32 s10, s51, s35
	v_add_u32_e32 v128, s10, v198
	v_add_u32_e32 v252, s37, v128
	s_waitcnt lgkmcnt(0)
	s_waitcnt vmcnt(0)
	s_barrier
	ds_read_b128 v[220:223], v253
	ds_read_b128 v[224:227], v253 offset:2048
	v_mfma_f32_16x16x32_bf16 v[44:47], v[240:243], v[134:137], v[44:47]
	v_mfma_f32_16x16x32_bf16 v[28:31], v[244:247], v[134:137], v[28:31]
	v_mfma_f32_16x16x32_bf16 v[12:15], v[248:251], v[134:137], v[12:15]
	ds_read_b128 v[134:137], v252 offset:32768
	v_mfma_f32_16x16x32_bf16 v[40:43], v[240:243], v[142:145], v[40:43]
	v_mfma_f32_16x16x32_bf16 v[24:27], v[244:247], v[142:145], v[24:27]
	v_mfma_f32_16x16x32_bf16 v[8:11], v[248:251], v[142:145], v[8:11]
	ds_read_b128 v[142:145], v252 offset:34816
	v_mfma_f32_16x16x32_bf16 v[36:39], v[240:243], v[146:149], v[36:39]
	v_mfma_f32_16x16x32_bf16 v[20:23], v[244:247], v[146:149], v[20:23]
	v_mfma_f32_16x16x32_bf16 v[4:7], v[248:251], v[146:149], v[4:7]
	ds_read_b128 v[146:149], v252 offset:36864
	v_mfma_f32_16x16x32_bf16 v[32:35], v[240:243], v[150:153], v[32:35]
	v_mfma_f32_16x16x32_bf16 v[16:19], v[244:247], v[150:153], v[16:19]
	v_mfma_f32_16x16x32_bf16 v[0:3], v[248:251], v[150:153], v[0:3]
	ds_read_b128 v[150:153], v252 offset:38912
	ds_read_b128 v[228:231], v253 offset:4096
	ds_read_b128 v[232:235], v253 offset:6144
	v_mov_b32_e32 v154, v253
	s_branch .Lmy_xf_1760

; DEVI f32x4 mfma16(bf16x8 a, bf16x8 b, f32x4 c) { return __builtin_amdgcn_mfma_f32_16x16x32_bf16(a, b, c, 0, 0, 0); }
; template <int MODE, class Epi>
; DEVI void gemm256_phase(int sw, const bf16_t* __restrict__ W, int ldw, const bf16_t* __restrict__ X, int ldx, int K, int nN, char* shm, const Epi& epi) {
;     ...
; #pragma unroll
;       for (int ks = 0; ks < 2; ++ks) {
;         const int kx = (wid >> 2) ? (1 - 2 * ks) * 1024 : 0;
;         bf16x8 At[8], Bf[4];
; #pragma unroll
;         for (int m = 0; m < 8; ++m) At[m] = *(const bf16x8*)(SAp + (2 * m + ks) * 1024 + kx);
; #pragma unroll
;         for (int n = 0; n < 4; ++n) Bf[n] = *(const bf16x8*)(SBp + (2 * n + ks) * 1024 + kx);
; #pragma unroll
;         for (int m = 0; m < 8; ++m)
; #pragma unroll
;           for (int n = 0; n < 4; ++n) acc[m][n] = mfma16(At[m], Bf[n], acc[m][n]);
;         __builtin_amdgcn_sched_barrier(0);
;         if (ks == 0 && wid >= 4) {
;           if (st_own) stage(cur ^ 1, n0, m0, kt0 + t + 1);
;           else if (st_next) stage(cur ^ 1, n1, m1, kt1);
;         }
;       }
;       asm volatile("s_waitcnt vmcnt(0)" ::: "memory");
;       __syncthreads();
.LBB0_1800:
.Lmy_xs_1801:
	s_waitcnt lgkmcnt(2)
	v_mfma_f32_16x16x32_bf16 v[124:127], v[220:223], v[134:137], v[124:127]
	v_mfma_f32_16x16x32_bf16 v[120:123], v[220:223], v[142:145], v[120:123]
	v_mfma_f32_16x16x32_bf16 v[116:119], v[220:223], v[146:149], v[116:119]
	v_mfma_f32_16x16x32_bf16 v[112:115], v[220:223], v[150:153], v[112:115]
	ds_read_b128 v[236:239], v154 offset:9216
	s_waitcnt lgkmcnt(3)
	v_mfma_f32_16x16x32_bf16 v[108:111], v[224:227], v[134:137], v[108:111]
	v_mfma_f32_16x16x32_bf16 v[104:107], v[224:227], v[142:145], v[104:107]
	v_mfma_f32_16x16x32_bf16 v[100:103], v[224:227], v[146:149], v[100:103]
	v_mfma_f32_16x16x32_bf16 v[96:99], v[224:227], v[150:153], v[96:99]
	ds_read_b128 v[240:243], v154 offset:11264
	s_waitcnt lgkmcnt(3)
	v_mfma_f32_16x16x32_bf16 v[92:95], v[228:231], v[134:137], v[92:95]
	v_mfma_f32_16x16x32_bf16 v[88:91], v[228:231], v[142:145], v[88:91]
	v_mfma_f32_16x16x32_bf16 v[84:87], v[228:231], v[146:149], v[84:87]
	v_mfma_f32_16x16x32_bf16 v[80:83], v[228:231], v[150:153], v[80:83]
	ds_read_b128 v[244:247], v154 offset:13312
	s_waitcnt lgkmcnt(3)
	v_mfma_f32_16x16x32_bf16 v[76:79], v[232:235], v[134:137], v[76:79]
	v_mfma_f32_16x16x32_bf16 v[72:75], v[232:235], v[142:145], v[72:75]
	v_mfma_f32_16x16x32_bf16 v[68:71], v[232:235], v[146:149], v[68:71]
	v_mfma_f32_16x16x32_bf16 v[64:67], v[232:235], v[150:153], v[64:67]
	ds_read_b128 v[248:251], v154 offset:15360
	s_waitcnt lgkmcnt(3)
	v_mfma_f32_16x16x32_bf16 v[60:63], v[236:239], v[134:137], v[60:63]
	v_mfma_f32_16x16x32_bf16 v[56:59], v[236:239], v[142:145], v[56:59]
	v_mfma_f32_16x16x32_bf16 v[52:55], v[236:239], v[146:149], v[52:55]
	v_mfma_f32_16x16x32_bf16 v[48:51], v[236:239], v[150:153], v[48:51]
	s_addk_i32 s69, 0x80
	s_cmp_eq_u32 s68, s70
	s_cbranch_scc1 .Lmy_xexit_1801
	s_add_i32 s2, s52, s70
	s_and_b32 s71, s2, 1
	s_add_i32 s70, s70, 1
	s_cmp_lt_i32 s70, s58
	s_cselect_b64 s[2:3], -1, 0
	s_cmp_ge_i32 s70, s58
	s_cselect_b64 s[36:37], -1, 0
	v_cndmask_b32_e64 v128, 0, 1, s[2:3]
	s_and_b64 s[36:37], s[28:29], s[36:37]
	s_and_b64 vcc, exec, s[0:1]
	v_cmp_ne_u32_e64 s[2:3], 1, v128
	s_lshl_b32 s38, s71, 16
	s_add_i32 s16, s38, s49
	v_add_u32_e32 v129, s16, v194
	v_add_u32_e32 v253, s53, v129
	s_or_b32 s16, s38, s50
	v_add_u32_e32 v128, s16, v194
	v_add_u32_e32 v252, s53, v128
	s_waitcnt lgkmcnt(0)
	s_waitcnt vmcnt(0)
	s_barrier
	ds_read_b128 v[220:223], v253
	ds_read_b128 v[224:227], v253 offset:2048
	v_mfma_f32_16x16x32_bf16 v[44:47], v[240:243], v[134:137], v[44:47]
	v_mfma_f32_16x16x32_bf16 v[28:31], v[244:247], v[134:137], v[28:31]
	v_mfma_f32_16x16x32_bf16 v[12:15], v[248:251], v[134:137], v[12:15]
	ds_read_b128 v[134:137], v252 offset:32768
	v_mfma_f32_16x16x32_bf16 v[40:43], v[240:243], v[142:145], v[40:43]
	v_mfma_f32_16x16x32_bf16 v[24:27], v[244:247], v[142:145], v[24:27]
	v_mfma_f32_16x16x32_bf16 v[8:11], v[248:251], v[142:145], v[8:11]
	ds_read_b128 v[142:145], v252 offset:34816
	v_mfma_f32_16x16x32_bf16 v[36:39], v[240:243], v[146:149], v[36:39]
	v_mfma_f32_16x16x32_bf16 v[20:23], v[244:247], v[146:149], v[20:23]
	v_mfma_f32_16x16x32_bf16 v[4:7], v[248:251], v[146:149], v[4:7]
	ds_read_b128 v[146:149], v252 offset:36864
	v_mfma_f32_16x16x32_bf16 v[32:35], v[240:243], v[150:153], v[32:35]
	v_mfma_f32_16x16x32_bf16 v[16:19], v[244:247], v[150:153], v[16:19]
	v_mfma_f32_16x16x32_bf16 v[0:3], v[248:251], v[150:153], v[0:3]
	ds_read_b128 v[150:153], v252 offset:38912
	ds_read_b128 v[228:231], v253 offset:4096
	ds_read_b128 v[232:235], v253 offset:6144
	v_mov_b32_e32 v154, v253
	s_branch .Lmy_xf_1801
